# static priority raise for the straggler: mLSTM wave 0 (carries the per-chunk serial extras) runs at s_setprio 1 for its unit; timing only, bit-identical
# baseline (speedup 1.0000x reference)
; #define LAS __attribute__((address_space(3)))
; __device__ __forceinline__ int launder_i(int x) { asm volatile("" : "+v"(x)); return x; }
; #define conv_w KIN(5)
; #define conv_b KIN(6)
; __device__ __forceinline__ void mlstm_unit(int unit, int l, const bf16_t* proj, const float* gif, const float* conv_w, const float* conv_b, bf16_t* mpart, float* dpart, int gplanes, LAS unsigned char* lds) {
;     const int tid = launder_i(threadIdx.x), lane = tid & 63, wid = __builtin_amdgcn_readfirstlane(tid >> 6);
;     const int b = unit >> 4, h = (unit >> 2) & 3, dq = unit & 3;
;     const int g = lane >> 4, c16 = lane & 15;
;     LAS bf16_t* Q = (LAS bf16_t*)(lds);
;     LAS bf16_t* KK = (LAS bf16_t*)(lds + 9216);
;     LAS bf16_t* V1 = (LAS bf16_t*)(lds + 18432);
;     LAS bf16_t* VW = (LAS bf16_t*)(lds + 52224);
;     LAS bf16_t* ST = (LAS bf16_t*)(lds + 86016);
;     LAS bf16_t* AS = (LAS bf16_t*)(lds + 122880);
;     LAS float* CWL = (LAS float*)(lds + 132096);
;     LAS float* tabs = (LAS float*)(lds + 134656);
;     LAS float* nvec = tabs + 384;
;     LAS float* dsum = nvec + 64;
;     LAS float* qn = dsum + 128;
;     LAS float* npart = qn + 64;
;     for (int i = tid; i < 256 * 72 / 2; i += NTHREADS) ((LAS unsigned*)ST)[i] = 0u;
;     if (tid < 64) nvec[tid] = 0.f;
.LBB0_397:
	s_mov_b64 s[4:5], s[0:1]
	s_load_dwordx2 s[40:41], s[4:5], 0xc0
	s_mov_b64 s[4:5], s[0:1]
	s_load_dwordx2 s[42:43], s[4:5], 0xc0
	s_mov_b64 s[4:5], s[0:1]
	s_load_dwordx2 s[48:49], s[4:5], 0x28
	s_mov_b64 s[4:5], s[0:1]
	s_load_dwordx2 s[44:45], s[4:5], 0x30
	s_mov_b64 s[4:5], s[0:1]
	s_load_dwordx2 s[88:89], s[4:5], 0xc0
	s_mov_b64 s[4:5], s[0:1]
	s_load_dwordx2 s[76:77], s[4:5], 0xc0
	v_mov_b32_e32 v112, v252
	s_movk_i32 s4, 0x2400
	v_ashrrev_i32_e32 v1, 6, v112
	v_cmp_gt_i32_e32 vcc, s4, v112
	v_readfirstlane_b32 s5, v1
	s_nop 0
	s_cmp_lg_u32 s5, 0
	s_cbranch_scc1 .Lml_prio_skip
	s_setprio 1
.Lml_prio_skip:
	s_and_saveexec_b64 s[38:39], vcc
	s_cbranch_execz .LBB0_400
	v_readlane_b32 s4, v254, 58
	v_add_u32_e32 v2, 0xfffffe00, v112
	s_mov_b64 s[46:47], 0
	v_lshl_add_u32 v3, v112, 2, s4

; #define conv_w KIN(5)
; #define conv_b KIN(6)
; __global__ void __launch_bounds__(NTHREADS, 2) fwd_megakernel(Params P) {
;     ...
;             if (bid < gm) { for (int rep = 0; rep < REP_M; ++rep) for (int u = bid; u < 64; u += gm) {
;     ...
;  mlstm_unit(u, l, B_PROJ, B_GIF, conv_w, conv_b, B_MPART + (size_t)(u & 3) * T * 1024, B_DPART + (size_t)(u & 3) * T * 4, (l > 0 && G == 256) ? 8 : 1, lds);
;     ...
;  } }
.LBB0_488:
	s_setprio 0
	v_readlane_b32 s88, v255, 26
	v_readlane_b32 s84, v255, 34
	v_readlane_b32 s82, v255, 38
	v_readlane_b32 s86, v255, 24
	v_readlane_b32 s89, v255, 27
	v_readlane_b32 s85, v255, 35
	v_readlane_b32 s83, v255, 39
	v_readlane_b32 s87, v255, 25
